# grid barrier: write-through stores (no L2 write-back) and the last XCD leader releases all XCD generation words directly
# speedup vs baseline: 1.0039x; 1.0039x over previous
.LBB0_461:
	s_andn2_saveexec_b64 s[4:5], s[4:5]
	s_cbranch_execz .LBB0_481
	s_mov_b64 s[4:5], exec
	v_mov_b32_e32 v8, v3
	s_waitcnt lgkmcnt(0)
	s_waitcnt vmcnt(0)
	v_mbcnt_lo_u32_b32 v3, s4, 0
	v_mbcnt_hi_u32_b32 v3, s5, v3
	v_cmp_eq_u32_e32 vcc, 0, v3
	s_and_saveexec_b64 s[6:7], vcc
	s_cbranch_execz .LBB0_464
	s_bcnt1_i32_b64 s4, s[4:5]
	v_mov_b32_e32 v5, s4
	v_readlane_b32 s4, v253, 9
	v_readlane_b32 s5, v253, 10
	s_nop 4
	global_atomic_add v5, v4, v5, s[4:5] sc0
.LBB0_464:
	s_or_b64 exec, exec, s[6:7]
	s_waitcnt vmcnt(0)
	v_readfirstlane_b32 s4, v5
	v_cvt_f32_u32_e32 v5, v2
	v_sub_u32_e32 v6, 0, v2
	v_add_u32_e32 v3, s4, v3
	s_mov_b64 s[6:7], -1
	v_rcp_iflag_f32_e32 v5, v5
	s_nop 0
	v_mul_f32_e32 v5, 0x4f7ffffe, v5
	v_cvt_u32_f32_e32 v5, v5
	v_mul_lo_u32 v6, v6, v5
	v_mul_hi_u32 v6, v5, v6
	v_add_u32_e32 v5, v5, v6
	v_mul_hi_u32 v5, v3, v5
	v_mul_lo_u32 v6, v5, v2
	v_sub_u32_e32 v6, v3, v6
	v_cmp_ge_u32_e32 vcc, v6, v2
	v_add_u32_e32 v7, 1, v5
	v_add_u32_e32 v3, 1, v3
	v_cndmask_b32_e32 v5, v5, v7, vcc
	v_sub_u32_e32 v7, v6, v2
	v_cndmask_b32_e32 v6, v6, v7, vcc
	v_cmp_ge_u32_e32 vcc, v6, v2
	v_add_u32_e32 v6, 1, v5
	s_nop 0
	v_cndmask_b32_e32 v5, v5, v6, vcc
	v_mul_lo_u32 v6, v2, v5
	v_add_u32_e32 v2, v6, v2
	v_cmp_ne_u32_e32 vcc, v3, v2
	s_and_saveexec_b64 s[4:5], vcc
	s_cbranch_execz .Lrl_last_1
	s_mov_b32 s18, 0
.Lrl_poll_1:
	global_load_dword v2, v4, s[82:83] sc1
	s_waitcnt vmcnt(0)
	v_cmp_ne_u32_e32 vcc, v2, v8
	s_cbranch_vccnz .LBB0_480
	s_sleep 1
	s_add_i32 s18, s18, 1
	s_cmp_lt_u32 s18, 0x400000
	s_cbranch_scc1 .Lrl_poll_1
	s_branch .LBB0_480
.Lrl_last_1:
	s_or_b64 exec, exec, s[4:5]
	s_add_u32 s6, s42, 0xffffef00
	s_addc_u32 s7, s43, -1
	global_atomic_add v4, v238, s[42:43]
	global_atomic_add v4, v238, s[6:7]
	global_atomic_add v4, v238, s[6:7] offset:256
	global_atomic_add v4, v238, s[6:7] offset:512
	global_atomic_add v4, v238, s[6:7] offset:768
	global_atomic_add v4, v238, s[6:7] offset:1024
	global_atomic_add v4, v238, s[6:7] offset:1280
	global_atomic_add v4, v238, s[6:7] offset:1536
	global_atomic_add v4, v238, s[6:7] offset:1792
	global_atomic_add v4, v238, s[6:7] offset:2048
	global_atomic_add v4, v238, s[6:7] offset:2304
	global_atomic_add v4, v238, s[6:7] offset:2560
	global_atomic_add v4, v238, s[6:7] offset:2816
	global_atomic_add v4, v238, s[6:7] offset:3072
	global_atomic_add v4, v238, s[6:7] offset:3328
	global_atomic_add v4, v238, s[6:7] offset:3584
	global_atomic_add v4, v238, s[6:7] offset:3840

.LBB0_551:
	s_andn2_saveexec_b64 s[6:7], s[6:7]
	s_cbranch_execz .LBB0_571
	s_mov_b64 s[6:7], exec
	v_mov_b32_e32 v8, v3
	s_waitcnt lgkmcnt(0)
	s_waitcnt vmcnt(0)
	v_mbcnt_lo_u32_b32 v3, s6, 0
	v_mbcnt_hi_u32_b32 v3, s7, v3
	v_cmp_eq_u32_e32 vcc, 0, v3
	s_and_saveexec_b64 s[8:9], vcc
	s_cbranch_execz .LBB0_554
	s_bcnt1_i32_b64 s6, s[6:7]
	v_mov_b32_e32 v5, s6
	v_readlane_b32 s6, v253, 9
	v_readlane_b32 s7, v253, 10
	s_nop 4
	global_atomic_add v5, v4, v5, s[6:7] sc0
.LBB0_554:
	s_or_b64 exec, exec, s[8:9]
	s_waitcnt vmcnt(0)
	v_readfirstlane_b32 s6, v5
	v_cvt_f32_u32_e32 v5, v2
	v_sub_u32_e32 v6, 0, v2
	v_add_u32_e32 v3, s6, v3
	s_mov_b64 s[8:9], -1
	v_rcp_iflag_f32_e32 v5, v5
	s_nop 0
	v_mul_f32_e32 v5, 0x4f7ffffe, v5
	v_cvt_u32_f32_e32 v5, v5
	v_mul_lo_u32 v6, v6, v5
	v_mul_hi_u32 v6, v5, v6
	v_add_u32_e32 v5, v5, v6
	v_mul_hi_u32 v5, v3, v5
	v_mul_lo_u32 v6, v5, v2
	v_sub_u32_e32 v6, v3, v6
	v_cmp_ge_u32_e32 vcc, v6, v2
	v_add_u32_e32 v7, 1, v5
	v_add_u32_e32 v3, 1, v3
	v_cndmask_b32_e32 v5, v5, v7, vcc
	v_sub_u32_e32 v7, v6, v2
	v_cndmask_b32_e32 v6, v6, v7, vcc
	v_cmp_ge_u32_e32 vcc, v6, v2
	v_add_u32_e32 v6, 1, v5
	s_nop 0
	v_cndmask_b32_e32 v5, v5, v6, vcc
	v_mul_lo_u32 v6, v2, v5
	v_add_u32_e32 v2, v6, v2
	v_cmp_ne_u32_e32 vcc, v3, v2
	s_and_saveexec_b64 s[6:7], vcc
	s_cbranch_execz .Lrl_last_2
	s_mov_b32 s20, 0
.Lrl_poll_2:
	global_load_dword v2, v4, s[82:83] sc1
	s_waitcnt vmcnt(0)
	v_cmp_ne_u32_e32 vcc, v2, v8
	s_cbranch_vccnz .LBB0_570
	s_sleep 1
	s_add_i32 s20, s20, 1
	s_cmp_lt_u32 s20, 0x400000
	s_cbranch_scc1 .Lrl_poll_2
	s_branch .LBB0_570
.Lrl_last_2:
	s_or_b64 exec, exec, s[6:7]
	s_add_u32 s8, s42, 0xffffef00
	s_addc_u32 s9, s43, -1
	global_atomic_add v4, v238, s[42:43]
	global_atomic_add v4, v238, s[8:9]
	global_atomic_add v4, v238, s[8:9] offset:256
	global_atomic_add v4, v238, s[8:9] offset:512
	global_atomic_add v4, v238, s[8:9] offset:768
	global_atomic_add v4, v238, s[8:9] offset:1024
	global_atomic_add v4, v238, s[8:9] offset:1280
	global_atomic_add v4, v238, s[8:9] offset:1536
	global_atomic_add v4, v238, s[8:9] offset:1792
	global_atomic_add v4, v238, s[8:9] offset:2048
	global_atomic_add v4, v238, s[8:9] offset:2304
	global_atomic_add v4, v238, s[8:9] offset:2560
	global_atomic_add v4, v238, s[8:9] offset:2816
	global_atomic_add v4, v238, s[8:9] offset:3072
	global_atomic_add v4, v238, s[8:9] offset:3328
	global_atomic_add v4, v238, s[8:9] offset:3584
	global_atomic_add v4, v238, s[8:9] offset:3840
